# hand-written decode (6 sets, V loaded once + permlane16 share) with sc1 nt KV-cache loads
# baseline (speedup 1.0000x reference)
.Ldq_npret_2:
	global_load_dwordx4 v[64:67], v59, s[4:5] offset:-4096 sc1 nt
	global_load_dwordx4 v[68:71], v59, s[6:7] offset:-4096 sc1 nt
	global_load_dwordx4 v[72:75], v59, s[4:5] sc1 nt
	global_load_dwordx4 v[76:79], v59, s[6:7] sc1 nt
	s_add_i32 s23, s23, 1
	s_and_b32 s33, s23, 15
	s_cmp_eq_u32 s33, 0
	s_cbranch_scc1 .Ldq_np_3
	s_add_u32 s4, s4, 0x2000
	s_addc_u32 s5, s5, 0
	s_add_u32 s6, s6, 0x2000
	s_addc_u32 s7, s7, 0
.Ldq_npret_4:
	global_load_dwordx4 v[80:83], v59, s[4:5] offset:-4096 sc1 nt
	global_load_dwordx4 v[84:87], v59, s[6:7] offset:-4096 sc1 nt
	global_load_dwordx4 v[88:91], v59, s[4:5] sc1 nt
	global_load_dwordx4 v[92:95], v59, s[6:7] sc1 nt
	s_add_i32 s23, s23, 1
	s_and_b32 s33, s23, 15
	s_cmp_eq_u32 s33, 0
	s_cbranch_scc1 .Ldq_np_5
	s_add_u32 s4, s4, 0x2000
	s_addc_u32 s5, s5, 0
	s_add_u32 s6, s6, 0x2000
	s_addc_u32 s7, s7, 0
.Ldq_npret_6:
	global_load_dwordx4 v[96:99], v59, s[4:5] offset:-4096 sc1 nt
	global_load_dwordx4 v[100:103], v59, s[6:7] offset:-4096 sc1 nt
	global_load_dwordx4 v[104:107], v59, s[4:5] sc1 nt
	global_load_dwordx4 v[108:111], v59, s[6:7] sc1 nt
	s_add_i32 s23, s23, 1
	s_and_b32 s33, s23, 15
	s_cmp_eq_u32 s33, 0
	s_cbranch_scc1 .Ldq_np_7
	s_add_u32 s4, s4, 0x2000
	s_addc_u32 s5, s5, 0
	s_add_u32 s6, s6, 0x2000
	s_addc_u32 s7, s7, 0
.Ldq_npret_8:
	global_load_dwordx4 v[112:115], v59, s[4:5] offset:-4096 sc1 nt
	global_load_dwordx4 v[116:119], v59, s[6:7] offset:-4096 sc1 nt
	global_load_dwordx4 v[120:123], v59, s[4:5] sc1 nt
	global_load_dwordx4 v[124:127], v59, s[6:7] sc1 nt
	s_add_i32 s23, s23, 1
	s_and_b32 s33, s23, 15
	s_cmp_eq_u32 s33, 0
	s_cbranch_scc1 .Ldq_np_9
	s_add_u32 s4, s4, 0x2000
	s_addc_u32 s5, s5, 0
	s_add_u32 s6, s6, 0x2000
	s_addc_u32 s7, s7, 0
.Ldq_npret_10:
	global_load_dwordx4 v[128:131], v59, s[4:5] offset:-4096 sc1 nt
	global_load_dwordx4 v[132:135], v59, s[6:7] offset:-4096 sc1 nt
	global_load_dwordx4 v[136:139], v59, s[4:5] sc1 nt
	global_load_dwordx4 v[140:143], v59, s[6:7] sc1 nt
	s_movk_i32 s56, 20

.Ldq_npret_13:
	global_load_dwordx4 v[144:147], v59, s[4:5] offset:-4096 sc1 nt
	global_load_dwordx4 v[148:151], v59, s[6:7] offset:-4096 sc1 nt
	global_load_dwordx4 v[152:155], v59, s[4:5] sc1 nt
	global_load_dwordx4 v[156:159], v59, s[6:7] sc1 nt
	s_add_i32 s39, s39, 1
	s_lshr_b32 s33, s39, 4
	s_cmp_eq_u32 s33, 7
	s_cselect_b32 s36, s37, 0
	s_waitcnt vmcnt(21)
	v_mul_f32_e32 v212, v40, v64
	v_mul_f32_e32 v213, v44, v64
	v_mul_f32_e32 v214, v48, v64
	v_mul_f32_e32 v215, v52, v64
	v_mul_f32_e32 v216, v40, v72
	v_mul_f32_e32 v217, v44, v72
	v_mul_f32_e32 v218, v48, v72
	v_mul_f32_e32 v219, v52, v72
	v_fmac_f32_e32 v212, v65, v41
	v_fmac_f32_e32 v213, v65, v45
	v_fmac_f32_e32 v214, v65, v49
	v_fmac_f32_e32 v215, v65, v53
	v_fmac_f32_e32 v216, v73, v41
	v_fmac_f32_e32 v217, v73, v45
	v_fmac_f32_e32 v218, v73, v49
	v_fmac_f32_e32 v219, v73, v53
	v_fmac_f32_e32 v212, v66, v42
	v_fmac_f32_e32 v213, v66, v46
	v_fmac_f32_e32 v214, v66, v50
	v_fmac_f32_e32 v215, v66, v54
	v_fmac_f32_e32 v216, v74, v42
	v_fmac_f32_e32 v217, v74, v46
	v_fmac_f32_e32 v218, v74, v50
	v_fmac_f32_e32 v219, v74, v54
	v_fmac_f32_e32 v212, v67, v43
	v_fmac_f32_e32 v213, v67, v47
	v_fmac_f32_e32 v214, v67, v51
	v_fmac_f32_e32 v215, v67, v55
	v_fmac_f32_e32 v216, v75, v43
	v_fmac_f32_e32 v217, v75, v47
	v_fmac_f32_e32 v218, v75, v51
	v_fmac_f32_e32 v219, v75, v55
	v_cndmask_b32_e64 v241, v212, v213, s[8:9]
	v_cndmask_b32_e64 v245, v216, v217, s[8:9]
	v_cndmask_b32_e64 v243, v214, v215, s[8:9]
	v_cndmask_b32_e64 v247, v218, v219, s[8:9]
	v_cndmask_b32_e64 v240, v213, v212, s[8:9]
	v_cndmask_b32_e64 v244, v217, v216, s[8:9]
	v_cndmask_b32_e64 v242, v215, v214, s[8:9]
	v_cndmask_b32_e64 v246, v219, v218, s[8:9]
	v_add_f32_dpp v240, v241, v240 quad_perm:[1,0,3,2] row_mask:0xf bank_mask:0xf bound_ctrl:1
	v_add_f32_dpp v244, v245, v244 quad_perm:[1,0,3,2] row_mask:0xf bank_mask:0xf bound_ctrl:1
	v_add_f32_dpp v242, v243, v242 quad_perm:[1,0,3,2] row_mask:0xf bank_mask:0xf bound_ctrl:1
	v_add_f32_dpp v246, v247, v246 quad_perm:[1,0,3,2] row_mask:0xf bank_mask:0xf bound_ctrl:1
	v_cndmask_b32_e64 v213, v240, v242, s[34:35]
	v_cndmask_b32_e64 v217, v244, v246, s[34:35]
	v_cndmask_b32_e64 v212, v242, v240, s[34:35]
	v_cndmask_b32_e64 v216, v246, v244, s[34:35]
	s_nop 0
	v_add_f32_dpp v212, v213, v212 quad_perm:[2,3,0,1] row_mask:0xf bank_mask:0xf bound_ctrl:1
	v_add_f32_dpp v216, v217, v216 quad_perm:[2,3,0,1] row_mask:0xf bank_mask:0xf bound_ctrl:1
	s_nop 0
	v_add_f32_dpp v212, v212, v212 row_ror:4 row_mask:0xf bank_mask:0xf bound_ctrl:1
	v_add_f32_dpp v216, v216, v216 row_ror:4 row_mask:0xf bank_mask:0xf bound_ctrl:1
	s_nop 0
	v_add_f32_dpp v212, v212, v212 row_ror:8 row_mask:0xf bank_mask:0xf bound_ctrl:1
	v_add_f32_dpp v216, v216, v216 row_ror:8 row_mask:0xf bank_mask:0xf bound_ctrl:1
	s_cmp_lg_u32 s36, 0
	s_cbranch_scc1 .Ldq_bias_14

.Ldq_npret_21:
	global_load_dwordx4 v[64:67], v59, s[4:5] offset:-4096 sc1 nt
	global_load_dwordx4 v[68:71], v59, s[6:7] offset:-4096 sc1 nt
	global_load_dwordx4 v[72:75], v59, s[4:5] sc1 nt
	global_load_dwordx4 v[76:79], v59, s[6:7] sc1 nt
	s_add_i32 s39, s39, 1
	s_lshr_b32 s33, s39, 4
	s_cmp_eq_u32 s33, 7
	s_cselect_b32 s36, s37, 0
	s_waitcnt vmcnt(21)
	v_mul_f32_e32 v212, v40, v80
	v_mul_f32_e32 v213, v44, v80
	v_mul_f32_e32 v214, v48, v80
	v_mul_f32_e32 v215, v52, v80
	v_mul_f32_e32 v216, v40, v88
	v_mul_f32_e32 v217, v44, v88
	v_mul_f32_e32 v218, v48, v88
	v_mul_f32_e32 v219, v52, v88
	v_fmac_f32_e32 v212, v81, v41
	v_fmac_f32_e32 v213, v81, v45
	v_fmac_f32_e32 v214, v81, v49
	v_fmac_f32_e32 v215, v81, v53
	v_fmac_f32_e32 v216, v89, v41
	v_fmac_f32_e32 v217, v89, v45
	v_fmac_f32_e32 v218, v89, v49
	v_fmac_f32_e32 v219, v89, v53
	v_fmac_f32_e32 v212, v82, v42
	v_fmac_f32_e32 v213, v82, v46
	v_fmac_f32_e32 v214, v82, v50
	v_fmac_f32_e32 v215, v82, v54
	v_fmac_f32_e32 v216, v90, v42
	v_fmac_f32_e32 v217, v90, v46
	v_fmac_f32_e32 v218, v90, v50
	v_fmac_f32_e32 v219, v90, v54
	v_fmac_f32_e32 v212, v83, v43
	v_fmac_f32_e32 v213, v83, v47
	v_fmac_f32_e32 v214, v83, v51
	v_fmac_f32_e32 v215, v83, v55
	v_fmac_f32_e32 v216, v91, v43
	v_fmac_f32_e32 v217, v91, v47
	v_fmac_f32_e32 v218, v91, v51
	v_fmac_f32_e32 v219, v91, v55
	v_cndmask_b32_e64 v241, v212, v213, s[8:9]
	v_cndmask_b32_e64 v245, v216, v217, s[8:9]
	v_cndmask_b32_e64 v243, v214, v215, s[8:9]
	v_cndmask_b32_e64 v247, v218, v219, s[8:9]
	v_cndmask_b32_e64 v240, v213, v212, s[8:9]
	v_cndmask_b32_e64 v244, v217, v216, s[8:9]
	v_cndmask_b32_e64 v242, v215, v214, s[8:9]
	v_cndmask_b32_e64 v246, v219, v218, s[8:9]
	v_add_f32_dpp v240, v241, v240 quad_perm:[1,0,3,2] row_mask:0xf bank_mask:0xf bound_ctrl:1
	v_add_f32_dpp v244, v245, v244 quad_perm:[1,0,3,2] row_mask:0xf bank_mask:0xf bound_ctrl:1
	v_add_f32_dpp v242, v243, v242 quad_perm:[1,0,3,2] row_mask:0xf bank_mask:0xf bound_ctrl:1
	v_add_f32_dpp v246, v247, v246 quad_perm:[1,0,3,2] row_mask:0xf bank_mask:0xf bound_ctrl:1
	v_cndmask_b32_e64 v213, v240, v242, s[34:35]
	v_cndmask_b32_e64 v217, v244, v246, s[34:35]
	v_cndmask_b32_e64 v212, v242, v240, s[34:35]
	v_cndmask_b32_e64 v216, v246, v244, s[34:35]
	s_nop 0
	v_add_f32_dpp v212, v213, v212 quad_perm:[2,3,0,1] row_mask:0xf bank_mask:0xf bound_ctrl:1
	v_add_f32_dpp v216, v217, v216 quad_perm:[2,3,0,1] row_mask:0xf bank_mask:0xf bound_ctrl:1
	s_nop 0
	v_add_f32_dpp v212, v212, v212 row_ror:4 row_mask:0xf bank_mask:0xf bound_ctrl:1
	v_add_f32_dpp v216, v216, v216 row_ror:4 row_mask:0xf bank_mask:0xf bound_ctrl:1
	s_nop 0
	v_add_f32_dpp v212, v212, v212 row_ror:8 row_mask:0xf bank_mask:0xf bound_ctrl:1
	v_add_f32_dpp v216, v216, v216 row_ror:8 row_mask:0xf bank_mask:0xf bound_ctrl:1
	s_cmp_lg_u32 s36, 0
	s_cbranch_scc1 .Ldq_bias_22

.Ldq_npret_29:
	global_load_dwordx4 v[80:83], v59, s[4:5] offset:-4096 sc1 nt
	global_load_dwordx4 v[84:87], v59, s[6:7] offset:-4096 sc1 nt
	global_load_dwordx4 v[88:91], v59, s[4:5] sc1 nt
	global_load_dwordx4 v[92:95], v59, s[6:7] sc1 nt
	s_add_i32 s39, s39, 1
	s_lshr_b32 s33, s39, 4
	s_cmp_eq_u32 s33, 7
	s_cselect_b32 s36, s37, 0
	s_waitcnt vmcnt(21)
	v_mul_f32_e32 v212, v40, v96
	v_mul_f32_e32 v213, v44, v96
	v_mul_f32_e32 v214, v48, v96
	v_mul_f32_e32 v215, v52, v96
	v_mul_f32_e32 v216, v40, v104
	v_mul_f32_e32 v217, v44, v104
	v_mul_f32_e32 v218, v48, v104
	v_mul_f32_e32 v219, v52, v104
	v_fmac_f32_e32 v212, v97, v41
	v_fmac_f32_e32 v213, v97, v45
	v_fmac_f32_e32 v214, v97, v49
	v_fmac_f32_e32 v215, v97, v53
	v_fmac_f32_e32 v216, v105, v41
	v_fmac_f32_e32 v217, v105, v45
	v_fmac_f32_e32 v218, v105, v49
	v_fmac_f32_e32 v219, v105, v53
	v_fmac_f32_e32 v212, v98, v42
	v_fmac_f32_e32 v213, v98, v46
	v_fmac_f32_e32 v214, v98, v50
	v_fmac_f32_e32 v215, v98, v54
	v_fmac_f32_e32 v216, v106, v42
	v_fmac_f32_e32 v217, v106, v46
	v_fmac_f32_e32 v218, v106, v50
	v_fmac_f32_e32 v219, v106, v54
	v_fmac_f32_e32 v212, v99, v43
	v_fmac_f32_e32 v213, v99, v47
	v_fmac_f32_e32 v214, v99, v51
	v_fmac_f32_e32 v215, v99, v55
	v_fmac_f32_e32 v216, v107, v43
	v_fmac_f32_e32 v217, v107, v47
	v_fmac_f32_e32 v218, v107, v51
	v_fmac_f32_e32 v219, v107, v55
	v_cndmask_b32_e64 v241, v212, v213, s[8:9]
	v_cndmask_b32_e64 v245, v216, v217, s[8:9]
	v_cndmask_b32_e64 v243, v214, v215, s[8:9]
	v_cndmask_b32_e64 v247, v218, v219, s[8:9]
	v_cndmask_b32_e64 v240, v213, v212, s[8:9]
	v_cndmask_b32_e64 v244, v217, v216, s[8:9]
	v_cndmask_b32_e64 v242, v215, v214, s[8:9]
	v_cndmask_b32_e64 v246, v219, v218, s[8:9]
	v_add_f32_dpp v240, v241, v240 quad_perm:[1,0,3,2] row_mask:0xf bank_mask:0xf bound_ctrl:1
	v_add_f32_dpp v244, v245, v244 quad_perm:[1,0,3,2] row_mask:0xf bank_mask:0xf bound_ctrl:1
	v_add_f32_dpp v242, v243, v242 quad_perm:[1,0,3,2] row_mask:0xf bank_mask:0xf bound_ctrl:1
	v_add_f32_dpp v246, v247, v246 quad_perm:[1,0,3,2] row_mask:0xf bank_mask:0xf bound_ctrl:1
	v_cndmask_b32_e64 v213, v240, v242, s[34:35]
	v_cndmask_b32_e64 v217, v244, v246, s[34:35]
	v_cndmask_b32_e64 v212, v242, v240, s[34:35]
	v_cndmask_b32_e64 v216, v246, v244, s[34:35]
	s_nop 0
	v_add_f32_dpp v212, v213, v212 quad_perm:[2,3,0,1] row_mask:0xf bank_mask:0xf bound_ctrl:1
	v_add_f32_dpp v216, v217, v216 quad_perm:[2,3,0,1] row_mask:0xf bank_mask:0xf bound_ctrl:1
	s_nop 0
	v_add_f32_dpp v212, v212, v212 row_ror:4 row_mask:0xf bank_mask:0xf bound_ctrl:1
	v_add_f32_dpp v216, v216, v216 row_ror:4 row_mask:0xf bank_mask:0xf bound_ctrl:1
	s_nop 0
	v_add_f32_dpp v212, v212, v212 row_ror:8 row_mask:0xf bank_mask:0xf bound_ctrl:1
	v_add_f32_dpp v216, v216, v216 row_ror:8 row_mask:0xf bank_mask:0xf bound_ctrl:1
	s_cmp_lg_u32 s36, 0
	s_cbranch_scc1 .Ldq_bias_30

.Ldq_npret_37:
	global_load_dwordx4 v[96:99], v59, s[4:5] offset:-4096 sc1 nt
	global_load_dwordx4 v[100:103], v59, s[6:7] offset:-4096 sc1 nt
	global_load_dwordx4 v[104:107], v59, s[4:5] sc1 nt
	global_load_dwordx4 v[108:111], v59, s[6:7] sc1 nt
	s_add_i32 s39, s39, 1
	s_lshr_b32 s33, s39, 4
	s_cmp_eq_u32 s33, 7
	s_cselect_b32 s36, s37, 0
	s_waitcnt vmcnt(21)
	v_mul_f32_e32 v212, v40, v112
	v_mul_f32_e32 v213, v44, v112
	v_mul_f32_e32 v214, v48, v112
	v_mul_f32_e32 v215, v52, v112
	v_mul_f32_e32 v216, v40, v120
	v_mul_f32_e32 v217, v44, v120
	v_mul_f32_e32 v218, v48, v120
	v_mul_f32_e32 v219, v52, v120
	v_fmac_f32_e32 v212, v113, v41
	v_fmac_f32_e32 v213, v113, v45
	v_fmac_f32_e32 v214, v113, v49
	v_fmac_f32_e32 v215, v113, v53
	v_fmac_f32_e32 v216, v121, v41
	v_fmac_f32_e32 v217, v121, v45
	v_fmac_f32_e32 v218, v121, v49
	v_fmac_f32_e32 v219, v121, v53
	v_fmac_f32_e32 v212, v114, v42
	v_fmac_f32_e32 v213, v114, v46
	v_fmac_f32_e32 v214, v114, v50
	v_fmac_f32_e32 v215, v114, v54
	v_fmac_f32_e32 v216, v122, v42
	v_fmac_f32_e32 v217, v122, v46
	v_fmac_f32_e32 v218, v122, v50
	v_fmac_f32_e32 v219, v122, v54
	v_fmac_f32_e32 v212, v115, v43
	v_fmac_f32_e32 v213, v115, v47
	v_fmac_f32_e32 v214, v115, v51
	v_fmac_f32_e32 v215, v115, v55
	v_fmac_f32_e32 v216, v123, v43
	v_fmac_f32_e32 v217, v123, v47
	v_fmac_f32_e32 v218, v123, v51
	v_fmac_f32_e32 v219, v123, v55
	v_cndmask_b32_e64 v241, v212, v213, s[8:9]
	v_cndmask_b32_e64 v245, v216, v217, s[8:9]
	v_cndmask_b32_e64 v243, v214, v215, s[8:9]
	v_cndmask_b32_e64 v247, v218, v219, s[8:9]
	v_cndmask_b32_e64 v240, v213, v212, s[8:9]
	v_cndmask_b32_e64 v244, v217, v216, s[8:9]
	v_cndmask_b32_e64 v242, v215, v214, s[8:9]
	v_cndmask_b32_e64 v246, v219, v218, s[8:9]
	v_add_f32_dpp v240, v241, v240 quad_perm:[1,0,3,2] row_mask:0xf bank_mask:0xf bound_ctrl:1
	v_add_f32_dpp v244, v245, v244 quad_perm:[1,0,3,2] row_mask:0xf bank_mask:0xf bound_ctrl:1
	v_add_f32_dpp v242, v243, v242 quad_perm:[1,0,3,2] row_mask:0xf bank_mask:0xf bound_ctrl:1
	v_add_f32_dpp v246, v247, v246 quad_perm:[1,0,3,2] row_mask:0xf bank_mask:0xf bound_ctrl:1
	v_cndmask_b32_e64 v213, v240, v242, s[34:35]
	v_cndmask_b32_e64 v217, v244, v246, s[34:35]
	v_cndmask_b32_e64 v212, v242, v240, s[34:35]
	v_cndmask_b32_e64 v216, v246, v244, s[34:35]
	s_nop 0
	v_add_f32_dpp v212, v213, v212 quad_perm:[2,3,0,1] row_mask:0xf bank_mask:0xf bound_ctrl:1
	v_add_f32_dpp v216, v217, v216 quad_perm:[2,3,0,1] row_mask:0xf bank_mask:0xf bound_ctrl:1
	s_nop 0
	v_add_f32_dpp v212, v212, v212 row_ror:4 row_mask:0xf bank_mask:0xf bound_ctrl:1
	v_add_f32_dpp v216, v216, v216 row_ror:4 row_mask:0xf bank_mask:0xf bound_ctrl:1
	s_nop 0
	v_add_f32_dpp v212, v212, v212 row_ror:8 row_mask:0xf bank_mask:0xf bound_ctrl:1
	v_add_f32_dpp v216, v216, v216 row_ror:8 row_mask:0xf bank_mask:0xf bound_ctrl:1
	s_cmp_lg_u32 s36, 0
	s_cbranch_scc1 .Ldq_bias_38

.Ldq_npret_45:
	global_load_dwordx4 v[112:115], v59, s[4:5] offset:-4096 sc1 nt
	global_load_dwordx4 v[116:119], v59, s[6:7] offset:-4096 sc1 nt
	global_load_dwordx4 v[120:123], v59, s[4:5] sc1 nt
	global_load_dwordx4 v[124:127], v59, s[6:7] sc1 nt
	s_add_i32 s39, s39, 1
	s_lshr_b32 s33, s39, 4
	s_cmp_eq_u32 s33, 7
	s_cselect_b32 s36, s37, 0
	s_waitcnt vmcnt(21)
	v_mul_f32_e32 v212, v40, v128
	v_mul_f32_e32 v213, v44, v128
	v_mul_f32_e32 v214, v48, v128
	v_mul_f32_e32 v215, v52, v128
	v_mul_f32_e32 v216, v40, v136
	v_mul_f32_e32 v217, v44, v136
	v_mul_f32_e32 v218, v48, v136
	v_mul_f32_e32 v219, v52, v136
	v_fmac_f32_e32 v212, v129, v41
	v_fmac_f32_e32 v213, v129, v45
	v_fmac_f32_e32 v214, v129, v49
	v_fmac_f32_e32 v215, v129, v53
	v_fmac_f32_e32 v216, v137, v41
	v_fmac_f32_e32 v217, v137, v45
	v_fmac_f32_e32 v218, v137, v49
	v_fmac_f32_e32 v219, v137, v53
	v_fmac_f32_e32 v212, v130, v42
	v_fmac_f32_e32 v213, v130, v46
	v_fmac_f32_e32 v214, v130, v50
	v_fmac_f32_e32 v215, v130, v54
	v_fmac_f32_e32 v216, v138, v42
	v_fmac_f32_e32 v217, v138, v46
	v_fmac_f32_e32 v218, v138, v50
	v_fmac_f32_e32 v219, v138, v54
	v_fmac_f32_e32 v212, v131, v43
	v_fmac_f32_e32 v213, v131, v47
	v_fmac_f32_e32 v214, v131, v51
	v_fmac_f32_e32 v215, v131, v55
	v_fmac_f32_e32 v216, v139, v43
	v_fmac_f32_e32 v217, v139, v47
	v_fmac_f32_e32 v218, v139, v51
	v_fmac_f32_e32 v219, v139, v55
	v_cndmask_b32_e64 v241, v212, v213, s[8:9]
	v_cndmask_b32_e64 v245, v216, v217, s[8:9]
	v_cndmask_b32_e64 v243, v214, v215, s[8:9]
	v_cndmask_b32_e64 v247, v218, v219, s[8:9]
	v_cndmask_b32_e64 v240, v213, v212, s[8:9]
	v_cndmask_b32_e64 v244, v217, v216, s[8:9]
	v_cndmask_b32_e64 v242, v215, v214, s[8:9]
	v_cndmask_b32_e64 v246, v219, v218, s[8:9]
	v_add_f32_dpp v240, v241, v240 quad_perm:[1,0,3,2] row_mask:0xf bank_mask:0xf bound_ctrl:1
	v_add_f32_dpp v244, v245, v244 quad_perm:[1,0,3,2] row_mask:0xf bank_mask:0xf bound_ctrl:1
	v_add_f32_dpp v242, v243, v242 quad_perm:[1,0,3,2] row_mask:0xf bank_mask:0xf bound_ctrl:1
	v_add_f32_dpp v246, v247, v246 quad_perm:[1,0,3,2] row_mask:0xf bank_mask:0xf bound_ctrl:1
	v_cndmask_b32_e64 v213, v240, v242, s[34:35]
	v_cndmask_b32_e64 v217, v244, v246, s[34:35]
	v_cndmask_b32_e64 v212, v242, v240, s[34:35]
	v_cndmask_b32_e64 v216, v246, v244, s[34:35]
	s_nop 0
	v_add_f32_dpp v212, v213, v212 quad_perm:[2,3,0,1] row_mask:0xf bank_mask:0xf bound_ctrl:1
	v_add_f32_dpp v216, v217, v216 quad_perm:[2,3,0,1] row_mask:0xf bank_mask:0xf bound_ctrl:1
	s_nop 0
	v_add_f32_dpp v212, v212, v212 row_ror:4 row_mask:0xf bank_mask:0xf bound_ctrl:1
	v_add_f32_dpp v216, v216, v216 row_ror:4 row_mask:0xf bank_mask:0xf bound_ctrl:1
	s_nop 0
	v_add_f32_dpp v212, v212, v212 row_ror:8 row_mask:0xf bank_mask:0xf bound_ctrl:1
	v_add_f32_dpp v216, v216, v216 row_ror:8 row_mask:0xf bank_mask:0xf bound_ctrl:1
	s_cmp_lg_u32 s36, 0
	s_cbranch_scc1 .Ldq_bias_46

.Ldq_npret_53:
	global_load_dwordx4 v[128:131], v59, s[4:5] offset:-4096 sc1 nt
	global_load_dwordx4 v[132:135], v59, s[6:7] offset:-4096 sc1 nt
	global_load_dwordx4 v[136:139], v59, s[4:5] sc1 nt
	global_load_dwordx4 v[140:143], v59, s[6:7] sc1 nt
	s_add_i32 s39, s39, 1
	s_lshr_b32 s33, s39, 4
	s_cmp_eq_u32 s33, 7
	s_cselect_b32 s36, s37, 0
	s_waitcnt vmcnt(21)
	v_mul_f32_e32 v212, v40, v144
	v_mul_f32_e32 v213, v44, v144
	v_mul_f32_e32 v214, v48, v144
	v_mul_f32_e32 v215, v52, v144
	v_mul_f32_e32 v216, v40, v152
	v_mul_f32_e32 v217, v44, v152
	v_mul_f32_e32 v218, v48, v152
	v_mul_f32_e32 v219, v52, v152
	v_fmac_f32_e32 v212, v145, v41
	v_fmac_f32_e32 v213, v145, v45
	v_fmac_f32_e32 v214, v145, v49
	v_fmac_f32_e32 v215, v145, v53
	v_fmac_f32_e32 v216, v153, v41
	v_fmac_f32_e32 v217, v153, v45
	v_fmac_f32_e32 v218, v153, v49
	v_fmac_f32_e32 v219, v153, v53
	v_fmac_f32_e32 v212, v146, v42
	v_fmac_f32_e32 v213, v146, v46
	v_fmac_f32_e32 v214, v146, v50
	v_fmac_f32_e32 v215, v146, v54
	v_fmac_f32_e32 v216, v154, v42
	v_fmac_f32_e32 v217, v154, v46
	v_fmac_f32_e32 v218, v154, v50
	v_fmac_f32_e32 v219, v154, v54
	v_fmac_f32_e32 v212, v147, v43
	v_fmac_f32_e32 v213, v147, v47
	v_fmac_f32_e32 v214, v147, v51
	v_fmac_f32_e32 v215, v147, v55
	v_fmac_f32_e32 v216, v155, v43
	v_fmac_f32_e32 v217, v155, v47
	v_fmac_f32_e32 v218, v155, v51
	v_fmac_f32_e32 v219, v155, v55
	v_cndmask_b32_e64 v241, v212, v213, s[8:9]
	v_cndmask_b32_e64 v245, v216, v217, s[8:9]
	v_cndmask_b32_e64 v243, v214, v215, s[8:9]
	v_cndmask_b32_e64 v247, v218, v219, s[8:9]
	v_cndmask_b32_e64 v240, v213, v212, s[8:9]
	v_cndmask_b32_e64 v244, v217, v216, s[8:9]
	v_cndmask_b32_e64 v242, v215, v214, s[8:9]
	v_cndmask_b32_e64 v246, v219, v218, s[8:9]
	v_add_f32_dpp v240, v241, v240 quad_perm:[1,0,3,2] row_mask:0xf bank_mask:0xf bound_ctrl:1
	v_add_f32_dpp v244, v245, v244 quad_perm:[1,0,3,2] row_mask:0xf bank_mask:0xf bound_ctrl:1
	v_add_f32_dpp v242, v243, v242 quad_perm:[1,0,3,2] row_mask:0xf bank_mask:0xf bound_ctrl:1
	v_add_f32_dpp v246, v247, v246 quad_perm:[1,0,3,2] row_mask:0xf bank_mask:0xf bound_ctrl:1
	v_cndmask_b32_e64 v213, v240, v242, s[34:35]
	v_cndmask_b32_e64 v217, v244, v246, s[34:35]
	v_cndmask_b32_e64 v212, v242, v240, s[34:35]
	v_cndmask_b32_e64 v216, v246, v244, s[34:35]
	s_nop 0
	v_add_f32_dpp v212, v213, v212 quad_perm:[2,3,0,1] row_mask:0xf bank_mask:0xf bound_ctrl:1
	v_add_f32_dpp v216, v217, v216 quad_perm:[2,3,0,1] row_mask:0xf bank_mask:0xf bound_ctrl:1
	s_nop 0
	v_add_f32_dpp v212, v212, v212 row_ror:4 row_mask:0xf bank_mask:0xf bound_ctrl:1
	v_add_f32_dpp v216, v216, v216 row_ror:4 row_mask:0xf bank_mask:0xf bound_ctrl:1
	s_nop 0
	v_add_f32_dpp v212, v212, v212 row_ror:8 row_mask:0xf bank_mask:0xf bound_ctrl:1
	v_add_f32_dpp v216, v216, v216 row_ror:8 row_mask:0xf bank_mask:0xf bound_ctrl:1
	s_cmp_lg_u32 s36, 0
	s_cbranch_scc1 .Ldq_bias_54
